# P2a and P3c fp8 epilogues: wave owns 64 contiguous cols + DPP half-row exchange, 8 rows x 64B per store (on top of P7/P9 epilogue changes)
# speedup vs baseline: 1.0107x; 1.0001x over previous
; #define G8_STAGE(bufoff, gbase, NM) do { _Pragma("unroll") for (int _i = 0; _i < 2; ++_i) { \
;     const char* _b = (const char*)(gbase) + (_i ? p2##NM : (size_t)0); asm volatile("" : "+s"(_b));     \
;     __builtin_amdgcn_global_load_lds((const unsigned*)(_b + voff##NM), (LAS unsigned*)(lds + (bufoff) + ldsw + _i * 8192), 16, 0, 0); } } while (0)
; #define G8_WAIT_V(n) asm volatile("s_waitcnt vmcnt(" #n ")" ::: "memory")
; #define G8_BAR __builtin_amdgcn_s_barrier()
;     ...
;   const int wid = __builtin_amdgcn_readfirstlane(tid >> 6), lane = tid & 63, wr = wid >> 2, wc = wid & 3, fr = lane & 15, fq = lane >> 4;
;   const int nt = K / BK;
;   unsigned voffA, voffB;
;   { int R, C; stage_rc(tid * 16, R, C); const int Rb = (R & ~31) + perm32(R & 31); voffA = (unsigned)(R * lda + C) * 2u; voffB = (unsigned)(Rb * ldb + C) * 2u; }
;   const size_t p2A = (size_t)64 * lda * 2, p2B = (size_t)64 * ldb * 2;
;   const size_t kstep = (size_t)(BK * 2);
;   const size_t hstepA = (size_t)HALF * lda * 2, hstepB = (size_t)HALF * ldb * 2;
;   const unsigned ldsw = (unsigned)wid * 1024u;
;   const int aoff = lds_byte(wr * 64 + fr, fq * 8), boff = lds_byte(wc * 32 + fr, fq * 8);
;     ...
;   G8_WAIT_V(2); G8_BAR;
;   G8_STAGE(G8_SB(1, 0), cB + kstep, B); G8_STAGE(G8_SA(1, 0), cA + kstep, A); G8_STAGE(G8_SB(1, 1), cB + hstepB + kstep, B);
;   G8_WAIT_V(6); G8_BAR;
.LBB0_403:
	s_lshl_b32 s11, s11, 13
	s_lshl_b32 s5, s12, 13
	s_and_b32 s11, s11, 0x6000
	s_add_u32 s12, s36, 0x80
	s_addc_u32 s13, s37, 0
	s_waitcnt vmcnt(2)
	s_barrier
	s_add_i32 m0, s3, 0x18000
	v_and_b32_e32 v1, 15, v0
	v_lshl_add_u64 v[2:3], s[12:13], 0, v[130:131]
	s_add_u32 s12, s36, 0x20080
	s_addc_u32 s13, s37, 0
	global_load_lds_dwordx4 v[2:3], off
	s_add_i32 m0, s3, 0x1a000
	v_lshl_add_u64 v[2:3], s[12:13], 0, v[130:131]
	s_add_u32 s12, s34, 0x80
	s_addc_u32 s13, s35, 0
	global_load_lds_dwordx4 v[2:3], off
	s_add_i32 s48, s3, 0x8000
	v_lshl_add_u64 v[2:3], s[12:13], 0, v[128:129]
	s_add_u32 s12, s34, 0x20080
	s_mov_b32 m0, s48
	s_addc_u32 s13, s35, 0
	global_load_lds_dwordx4 v[2:3], off
	s_add_i32 s49, s3, 0xa000
	v_lshl_add_u64 v[2:3], s[12:13], 0, v[128:129]
	s_add_u32 s12, s36, 0x40080
	s_mov_b32 m0, s49
	s_addc_u32 s13, s37, 0
	global_load_lds_dwordx4 v[2:3], off
	s_add_i32 m0, s3, 0x1c000
	v_lshlrev_b32_e32 v1, 6, v1
	v_lshl_add_u64 v[2:3], s[12:13], 0, v[130:131]
	s_add_u32 s12, s36, 0x60080
	s_addc_u32 s13, s37, 0
	global_load_lds_dwordx4 v[2:3], off
	s_add_i32 m0, s3, 0x1e000
	v_lshl_add_u64 v[2:3], s[12:13], 0, v[130:131]
	global_load_lds_dwordx4 v[2:3], off
	v_and_b32_e32 v2, 48, v0
	v_lshlrev_b32_e32 v0, 2, v0
	v_and_b32_e32 v0, 32, v0
	v_or_b32_e32 v3, v1, v2
	v_bitop3_b32 v1, v1, v0, v2 bitop3:0x36
	s_waitcnt vmcnt(6)
	s_cmpk_lt_u32 s10, 0x100
	v_bitop3_b32 v0, v3, s5, v0 bitop3:0xde
	v_or_b32_e32 v138, s11, v1
	s_cselect_b64 s[10:11], -1, 0
	s_add_i32 s50, 0, 0x10000
	s_add_i32 s51, 0, 0x14000
	s_sext_i32_i8 s59, s6
	v_add_u32_e32 v139, s50, v138
	v_add_u32_e32 v140, 0x1000, v139
	v_add_u32_e32 v141, 0, v0
	v_mov_b32_e32 v142, 0x358637bd
	s_mov_b32 s52, 0x800000
	s_mov_b64 s[12:13], 0x80000
	s_mov_b32 s53, 0x80000
	s_mov_b64 s[14:15], 0x90000
	s_mov_b32 s54, 0x90000
	s_mov_b64 s[16:17], 0xa0000
	s_mov_b32 s55, 0xa0000
	s_mov_b64 s[20:21], 0xb0000
	s_mov_b32 s56, 0xb0000
	s_mov_b32 s57, 0
	s_mov_b64 s[24:25], s[34:35]
	s_mov_b64 s[26:27], s[36:37]
	s_barrier
	s_branch .LBB0_406

; #define G8_STAGE(bufoff, gbase, NM) do { _Pragma("unroll") for (int _i = 0; _i < 2; ++_i) { \
;     const char* _b = (const char*)(gbase) + (_i ? p2##NM : (size_t)0); asm volatile("" : "+s"(_b));     \
;     __builtin_amdgcn_global_load_lds((const unsigned*)(_b + voff##NM), (LAS unsigned*)(lds + (bufoff) + ldsw + _i * 8192), 16, 0, 0); } } while (0)
; #define G8_WAIT_V(n) asm volatile("s_waitcnt vmcnt(" #n ")" ::: "memory")
; #define G8_WAIT_L(n) asm volatile("s_waitcnt lgkmcnt(" #n ")" ::: "memory")
; #define G8_BAR __builtin_amdgcn_s_barrier()
; #define G8_SCHED __builtin_amdgcn_sched_barrier(0)
;     ...
;     for (int t = 0; t < nt; t += 2) {
;       const bool last = (t == nt - 2);
;       const char* a1 = cA + (size_t)(t + 1) * kstep + hstepA;
;       const char* a2 = last ? nA : cA + (size_t)(t + 2) * kstep; const char* b2 = last ? nB : cB + (size_t)(t + 2) * kstep;
;       const char* a3 = a2 + kstep; const char* b3 = b2 + kstep;
;       asm volatile("" : "+s"(a1), "+s"(a2), "+s"(b2), "+s"(a3), "+s"(b3));
;       G8_LDB(B0, 0, 0); G8_LDB(B1, 0, 1); G8_SCHED; G8_LDA(At, 0, 0); G8_STAGE(G8_SA(1, 1), a1, A);
;       const bool d0a = (BD == 0) || (BD == 1 && t < (nt >> 1)) || (BD == 2 && !(cur.pn & 1));
;       const bool d1a = (BD == 0) || (BD == 1 && t >= (nt >> 1)) || (BD == 2 && !(cur.pn & 1));
;       const bool d0b = (BD == 0) || (BD == 1 && t < (nt >> 1)) || (BD == 2 && (cur.pn & 1));
;       const bool d1b = (BD == 0) || (BD == 1 && t >= (nt >> 1)) || (BD == 2 && (cur.pn & 1));
;       G8_WAIT_V(8); G8_WAIT_L(0); G8_BAR; if (d0a) G8_MMA(0, 0, At, B0); if (d1a) G8_MMA(0, 1, At, B1); G8_BAR; G8_SCHED;
;       G8_LDA(At, 0, 1); G8_STAGE(G8_SB(0, 0), b2, B); G8_STAGE(G8_SB(0, 1), b2 + hstepB, B); G8_STAGE(G8_SA(0, 0), a2, A);
;       G8_WAIT_V(8); G8_WAIT_L(0); G8_BAR; if (d0a) G8_MMA(1, 0, At, B0); if (d1a) G8_MMA(1, 1, At, B1); G8_BAR; G8_SCHED;
.LBB0_413:
	s_add_u32 s44, s34, 0x40080
	s_addc_u32 s45, s35, 0
	s_add_u32 s34, s34, 0x100
	s_addc_u32 s35, s35, 0
	s_cmp_eq_u32 s23, 12
	s_cselect_b32 s40, s24, s34
	s_cselect_b32 s41, s25, s35
	s_cselect_b32 s43, s27, s6
	s_cselect_b32 s42, s26, s5
	s_add_u32 s36, s40, 0x80
	s_addc_u32 s37, s41, 0
	s_add_u32 s38, s42, 0x80
	s_addc_u32 s39, s43, 0
	ds_read_b128 v[144:147], v139
	ds_read_b128 v[148:151], v139 offset:1024
	ds_read_b128 v[152:155], v139 offset:2048
	ds_read_b128 v[156:159], v139 offset:3072
	ds_read_b128 v[160:163], v140
	ds_read_b128 v[164:167], v140 offset:1024
	ds_read_b128 v[168:171], v140 offset:2048
	ds_read_b128 v[172:175], v140 offset:3072
	s_add_i32 m0, s3, 0xc000
	s_mov_b64 s[60:61], s[44:45]
	s_add_u32 s44, s44, 0x20000
	ds_read_b128 v[176:179], v141
	ds_read_b128 v[180:183], v141 offset:1024
	ds_read_b128 v[184:187], v141 offset:2048
	ds_read_b128 v[188:191], v141 offset:3072
	ds_read_b128 v[192:195], v141 offset:4096
	ds_read_b128 v[196:199], v141 offset:5120
	ds_read_b128 v[202:205], v141 offset:6144
	ds_read_b128 v[206:209], v141 offset:7168
	s_addc_u32 s45, s45, 0
	v_lshl_add_u64 v[134:135], s[60:61], 0, v[128:129]
	global_load_lds_dwordx4 v[134:135], off
	s_add_i32 m0, s3, 0xe000
	v_lshl_add_u64 v[134:135], s[44:45], 0, v[128:129]
	global_load_lds_dwordx4 v[134:135], off
	s_waitcnt vmcnt(8)
	s_waitcnt lgkmcnt(0)
	s_barrier
	s_setprio 1
	s_waitcnt lgkmcnt(0)
	v_mfma_f32_16x16x128_f8f6f4 v[124:127], v[144:151], v[176:183], v[124:127]
	v_mfma_f32_16x16x128_f8f6f4 v[120:123], v[152:159], v[176:183], v[120:123]
	v_mfma_f32_16x16x128_f8f6f4 v[108:111], v[144:151], v[184:191], v[108:111]
	v_mfma_f32_16x16x128_f8f6f4 v[104:107], v[152:159], v[184:191], v[104:107]
	v_mfma_f32_16x16x128_f8f6f4 v[134:137], v[144:151], v[192:199], v[92:95]
	v_mfma_f32_16x16x128_f8f6f4 v[210:213], v[152:159], v[192:199], v[88:91]
	v_mfma_f32_16x16x128_f8f6f4 v[214:217], v[144:151], v[202:209], v[76:79]
	v_mfma_f32_16x16x128_f8f6f4 v[218:221], v[152:159], v[202:209], v[72:75]
	s_setprio 0
	s_setprio 1
	v_mfma_f32_16x16x128_f8f6f4 v[116:119], v[160:167], v[176:183], v[116:119]
	v_mfma_f32_16x16x128_f8f6f4 v[112:115], v[168:175], v[176:183], v[112:115]
	v_mfma_f32_16x16x128_f8f6f4 v[100:103], v[160:167], v[184:191], v[100:103]
	v_mfma_f32_16x16x128_f8f6f4 v[96:99], v[168:175], v[184:191], v[96:99]
	v_mfma_f32_16x16x128_f8f6f4 v[176:179], v[160:167], v[192:199], v[84:87]
	v_mfma_f32_16x16x128_f8f6f4 v[180:183], v[168:175], v[192:199], v[80:83]
	v_mfma_f32_16x16x128_f8f6f4 v[184:187], v[160:167], v[202:209], v[68:71]
	v_mfma_f32_16x16x128_f8f6f4 v[188:191], v[168:175], v[202:209], v[64:67]
	s_setprio 0
	s_barrier
	s_mov_b64 s[44:45], s[42:43]
	s_nop 3
	ds_read_b128 v[64:67], v141 offset:16384
	ds_read_b128 v[68:71], v141 offset:17408
	ds_read_b128 v[72:75], v141 offset:18432
	ds_read_b128 v[76:79], v141 offset:19456
	ds_read_b128 v[80:83], v141 offset:20480
	ds_read_b128 v[84:87], v141 offset:21504
	ds_read_b128 v[88:91], v141 offset:22528
	ds_read_b128 v[92:95], v141 offset:23552
	s_add_i32 s60, s50, s0
	v_lshl_add_u64 v[192:193], s[44:45], 0, v[130:131]
	s_add_u32 s44, s42, 0x20000
	s_mov_b32 m0, s60
	s_addc_u32 s45, s43, 0
	global_load_lds_dwordx4 v[192:193], off
	s_add_i32 m0, s60, 0x2000
	v_lshl_add_u64 v[192:193], s[44:45], 0, v[130:131]
	s_add_u32 s44, s42, 0x40000
	s_addc_u32 s45, s43, 0
	global_load_lds_dwordx4 v[192:193], off
	s_nop 0
	v_lshl_add_u64 v[192:193], s[44:45], 0, v[130:131]
	s_add_i32 s44, s51, s0
	s_add_u32 s42, s42, 0x60000
	s_mov_b32 m0, s44
	s_addc_u32 s43, s43, 0
	global_load_lds_dwordx4 v[192:193], off
	s_add_i32 m0, s44, 0x2000
	v_lshl_add_u64 v[192:193], s[42:43], 0, v[130:131]
	s_mov_b64 s[42:43], s[40:41]
	global_load_lds_dwordx4 v[192:193], off
	s_mov_b32 m0, s3
	v_lshl_add_u64 v[192:193], s[42:43], 0, v[128:129]
	s_add_u32 s42, s40, 0x20000
	s_addc_u32 s43, s41, 0
	global_load_lds_dwordx4 v[192:193], off
	s_mov_b32 m0, s33
	v_lshl_add_u64 v[192:193], s[42:43], 0, v[128:129]
	global_load_lds_dwordx4 v[192:193], off
	s_waitcnt vmcnt(8)
	s_waitcnt lgkmcnt(0)
	s_barrier
	s_setprio 1
	s_waitcnt lgkmcnt(0)
	v_mfma_f32_16x16x128_f8f6f4 v[60:63], v[144:151], v[64:71], v[60:63]
	v_mfma_f32_16x16x128_f8f6f4 v[56:59], v[152:159], v[64:71], v[56:59]
	v_mfma_f32_16x16x128_f8f6f4 v[192:195], v[144:151], v[72:79], v[44:47]
	v_mfma_f32_16x16x128_f8f6f4 v[196:199], v[152:159], v[72:79], v[40:43]
	v_mfma_f32_16x16x128_f8f6f4 v[202:205], v[144:151], v[80:87], v[28:31]
	v_mfma_f32_16x16x128_f8f6f4 v[206:209], v[152:159], v[80:87], v[24:27]
	v_mfma_f32_16x16x128_f8f6f4 v[222:225], v[144:151], v[88:95], v[12:15]
	v_mfma_f32_16x16x128_f8f6f4 v[226:229], v[152:159], v[88:95], v[8:11]
	s_setprio 0
	s_setprio 1
	v_mfma_f32_16x16x128_f8f6f4 v[52:55], v[160:167], v[64:71], v[52:55]
	v_mfma_f32_16x16x128_f8f6f4 v[48:51], v[168:175], v[64:71], v[48:51]
	v_mfma_f32_16x16x128_f8f6f4 v[230:233], v[160:167], v[72:79], v[36:39]
	v_mfma_f32_16x16x128_f8f6f4 v[234:237], v[168:175], v[72:79], v[32:35]
	v_mfma_f32_16x16x128_f8f6f4 v[238:241], v[160:167], v[80:87], v[20:23]
	v_mfma_f32_16x16x128_f8f6f4 v[242:245], v[168:175], v[80:87], v[16:19]
	v_mfma_f32_16x16x128_f8f6f4 v[246:249], v[160:167], v[88:95], v[4:7]
	v_mfma_f32_16x16x128_f8f6f4 v[250:253], v[168:175], v[88:95], v[0:3]
	s_setprio 0
	s_barrier
; #define G8_STAGE(bufoff, gbase, NM) do { _Pragma("unroll") for (int _i = 0; _i < 2; ++_i) { \
;     const char* _b = (const char*)(gbase) + (_i ? p2##NM : (size_t)0); asm volatile("" : "+s"(_b));     \
;     __builtin_amdgcn_global_load_lds((const unsigned*)(_b + voff##NM), (LAS unsigned*)(lds + (bufoff) + ldsw + _i * 8192), 16, 0, 0); } } while (0)
; #define G8_WAIT_V(n) asm volatile("s_waitcnt vmcnt(" #n ")" ::: "memory")
; #define G8_WAIT_L(n) asm volatile("s_waitcnt lgkmcnt(" #n ")" ::: "memory")
; #define G8_BAR __builtin_amdgcn_s_barrier()
; #define G8_SCHED __builtin_amdgcn_sched_barrier(0)
;     ...
;       G8_WAIT_V(8); G8_WAIT_L(0); G8_BAR; if (d0a) G8_MMA(1, 0, At, B0); if (d1a) G8_MMA(1, 1, At, B1); G8_BAR; G8_SCHED;
;       G8_LDB(B0, 1, 0); G8_LDB(B1, 1, 1); G8_SCHED; G8_LDA(At, 1, 0); G8_STAGE(G8_SA(0, 1), a2 + hstepA, A);
;       G8_WAIT_V(8); G8_WAIT_L(0); G8_BAR; if (d0b) G8_MMA(0, 0, At, B0); if (d1b) G8_MMA(0, 1, At, B1); G8_BAR; G8_SCHED;
;       G8_LDA(At, 1, 1); G8_STAGE(G8_SB(1, 0), b3, B); G8_STAGE(G8_SB(1, 1), b3 + hstepB, B); G8_STAGE(G8_SA(1, 0), a3, A);
;       G8_WAIT_V(8); G8_WAIT_L(0); G8_BAR; if (d0b) G8_MMA(1, 0, At, B0); if (d1b) G8_MMA(1, 1, At, B1); G8_BAR; G8_SCHED;
;     }
	s_add_i32 s44, 0, 0x18000
	v_add_u32_e32 v8, s44, v138
	s_add_i32 s45, 0, 0x1c000
	s_nop 1
	ds_read_b128 v[0:3], v8
	ds_read_b128 v[4:7], v8 offset:1024
	ds_read_b128 v[16:19], v8 offset:2048
	ds_read_b128 v[20:23], v8 offset:3072
	v_add_u32_e32 v8, 0x1000, v8
	ds_read_b128 v[144:147], v8
	ds_read_b128 v[148:151], v8 offset:1024
	ds_read_b128 v[152:155], v8 offset:2048
	ds_read_b128 v[156:159], v8 offset:3072
	s_add_u32 s42, s40, 0x40000
	s_addc_u32 s43, s41, 0
	s_add_u32 s40, s40, 0x60000
	s_mov_b32 m0, s46
	ds_read_b128 v[8:11], v141 offset:32768
	ds_read_b128 v[12:15], v141 offset:33792
	ds_read_b128 v[24:27], v141 offset:34816
	ds_read_b128 v[28:31], v141 offset:35840
	ds_read_b128 v[32:35], v141 offset:36864
	ds_read_b128 v[36:39], v141 offset:37888
	ds_read_b128 v[40:43], v141 offset:38912
	ds_read_b128 v[44:47], v141 offset:39936
	s_addc_u32 s41, s41, 0
	v_lshl_add_u64 v[64:65], s[42:43], 0, v[128:129]
	global_load_lds_dwordx4 v[64:65], off
	s_mov_b32 m0, s47
	v_lshl_add_u64 v[64:65], s[40:41], 0, v[128:129]
	global_load_lds_dwordx4 v[64:65], off
	s_waitcnt vmcnt(8)
	s_waitcnt lgkmcnt(0)
	s_barrier
	s_setprio 1
	s_waitcnt lgkmcnt(0)
	v_mfma_f32_16x16x128_f8f6f4 v[124:127], v[0:7], v[8:15], v[124:127]
	v_mfma_f32_16x16x128_f8f6f4 v[120:123], v[16:23], v[8:15], v[120:123]
	v_mfma_f32_16x16x128_f8f6f4 v[108:111], v[0:7], v[24:31], v[108:111]
	v_mfma_f32_16x16x128_f8f6f4 v[104:107], v[16:23], v[24:31], v[104:107]
	v_mfma_f32_16x16x128_f8f6f4 v[92:95], v[0:7], v[32:39], v[134:137]
	v_mfma_f32_16x16x128_f8f6f4 v[88:91], v[16:23], v[32:39], v[210:213]
	v_mfma_f32_16x16x128_f8f6f4 v[76:79], v[0:7], v[40:47], v[214:217]
	v_mfma_f32_16x16x128_f8f6f4 v[72:75], v[16:23], v[40:47], v[218:221]
	s_setprio 0
	s_setprio 1
	v_mfma_f32_16x16x128_f8f6f4 v[116:119], v[144:151], v[8:15], v[116:119]
	v_mfma_f32_16x16x128_f8f6f4 v[112:115], v[152:159], v[8:15], v[112:115]
	v_mfma_f32_16x16x128_f8f6f4 v[100:103], v[144:151], v[24:31], v[100:103]
	v_mfma_f32_16x16x128_f8f6f4 v[96:99], v[152:159], v[24:31], v[96:99]
	v_mfma_f32_16x16x128_f8f6f4 v[84:87], v[144:151], v[32:39], v[176:179]
	v_mfma_f32_16x16x128_f8f6f4 v[80:83], v[152:159], v[32:39], v[180:183]
	v_mfma_f32_16x16x128_f8f6f4 v[68:71], v[144:151], v[40:47], v[184:187]
	v_mfma_f32_16x16x128_f8f6f4 v[64:67], v[152:159], v[40:47], v[188:191]
	s_setprio 0
	s_barrier
	s_mov_b64 s[40:41], s[38:39]
	ds_read_b128 v[32:35], v141 offset:49152
	ds_read_b128 v[36:39], v141 offset:50176
	ds_read_b128 v[160:163], v141 offset:51200
	ds_read_b128 v[164:167], v141 offset:52224
	ds_read_b128 v[168:171], v141 offset:53248
	ds_read_b128 v[172:175], v141 offset:54272
	ds_read_b128 v[176:179], v141 offset:55296
	ds_read_b128 v[180:183], v141 offset:56320
	s_add_i32 s42, s44, s0
	v_lshl_add_u64 v[8:9], s[40:41], 0, v[130:131]
	s_add_u32 s40, s38, 0x20000
	s_mov_b32 m0, s42
	s_addc_u32 s41, s39, 0
	global_load_lds_dwordx4 v[8:9], off
	s_add_i32 m0, s42, 0x2000
	v_lshl_add_u64 v[8:9], s[40:41], 0, v[130:131]
	s_add_u32 s40, s38, 0x40000
	s_addc_u32 s41, s39, 0
	global_load_lds_dwordx4 v[8:9], off
	s_nop 0
	v_lshl_add_u64 v[8:9], s[40:41], 0, v[130:131]
	s_add_i32 s40, s45, s0
	s_add_u32 s38, s38, 0x60000
	s_mov_b32 m0, s40
	s_addc_u32 s39, s39, 0
	global_load_lds_dwordx4 v[8:9], off
	s_add_i32 m0, s40, 0x2000
	v_lshl_add_u64 v[8:9], s[38:39], 0, v[130:131]
	s_mov_b64 s[38:39], s[36:37]
	s_add_u32 s36, s36, 0x20000
	global_load_lds_dwordx4 v[8:9], off
	s_mov_b32 m0, s48
	v_lshl_add_u64 v[8:9], s[38:39], 0, v[128:129]
	s_addc_u32 s37, s37, 0
	global_load_lds_dwordx4 v[8:9], off
	s_mov_b32 m0, s49
	v_lshl_add_u64 v[8:9], s[36:37], 0, v[128:129]
	global_load_lds_dwordx4 v[8:9], off
	s_waitcnt vmcnt(8)
	s_waitcnt lgkmcnt(0)
	s_barrier
	s_setprio 1
	s_waitcnt lgkmcnt(0)
	v_mfma_f32_16x16x128_f8f6f4 v[60:63], v[0:7], v[32:39], v[60:63]
	v_mfma_f32_16x16x128_f8f6f4 v[56:59], v[16:23], v[32:39], v[56:59]
	v_mfma_f32_16x16x128_f8f6f4 v[44:47], v[0:7], v[160:167], v[192:195]
	v_mfma_f32_16x16x128_f8f6f4 v[40:43], v[16:23], v[160:167], v[196:199]
	v_mfma_f32_16x16x128_f8f6f4 v[28:31], v[0:7], v[168:175], v[202:205]
	v_mfma_f32_16x16x128_f8f6f4 v[24:27], v[16:23], v[168:175], v[206:209]
	v_mfma_f32_16x16x128_f8f6f4 v[12:15], v[0:7], v[176:183], v[222:225]
	v_mfma_f32_16x16x128_f8f6f4 v[8:11], v[16:23], v[176:183], v[226:229]
	s_setprio 0
	s_setprio 1
	v_mfma_f32_16x16x128_f8f6f4 v[52:55], v[144:151], v[32:39], v[52:55]
	v_mfma_f32_16x16x128_f8f6f4 v[48:51], v[152:159], v[32:39], v[48:51]
	v_mfma_f32_16x16x128_f8f6f4 v[36:39], v[144:151], v[160:167], v[230:233]
	v_mfma_f32_16x16x128_f8f6f4 v[32:35], v[152:159], v[160:167], v[234:237]
	v_mfma_f32_16x16x128_f8f6f4 v[20:23], v[144:151], v[168:175], v[238:241]
	v_mfma_f32_16x16x128_f8f6f4 v[16:19], v[152:159], v[168:175], v[242:245]
	v_mfma_f32_16x16x128_f8f6f4 v[4:7], v[144:151], v[176:183], v[246:249]
	v_mfma_f32_16x16x128_f8f6f4 v[0:3], v[152:159], v[176:183], v[250:253]
	s_setprio 0
	s_barrier
	s_add_i32 s23, s23, 2
	s_add_u32 s5, s5, 0x100
	s_addc_u32 s6, s6, 0
	s_cmp_gt_u32 s23, 13
	s_cbranch_scc0 .LBB0_413
	s_and_b64 vcc, exec, s[10:11]
	s_cbranch_vccz .LBB0_416
	s_barrier
;   __device__ __forceinline__ void operator()(const Acc& acc, const GUnit& u, int wr, int wc, int fr, int fq) const {
;     const int row0 = u.pm * 256 + wr * 64 + fr, pn = u.pn + pnoff;
; #pragma unroll
;     for (int ai = 0; ai < 2; ++ai)
; #pragma unroll
;       for (int m = 0; m < 4; ++m) {
;         const int row = row0 + ai * 128 + m * 16;
;         const float rs = rsqrtf(ss0[row] * (1.f / 2048.f) + EPS) * osc;
;         if (pn < 32) {
;           unsigned char* base = (unsigned char*)(pn < 16 ? q : z) + (size_t)row * 4096 + (pn & 15) * 256 + wc * 32 + 8 * fq;
; #pragma unroll
;           for (int bj = 0; bj < 2; ++bj) { const f32x4 a = acc[ai][bj][m][0] * rs, b = acc[ai][bj][m][1] * rs; u32x2 w;
;             w[0] = __builtin_amdgcn_cvt_pk_fp8_f32(a[0], a[1], 0, false); w[0] = __builtin_amdgcn_cvt_pk_fp8_f32(a[2], a[3], w[0], true);
;             w[1] = __builtin_amdgcn_cvt_pk_fp8_f32(b[0], b[1], 0, false); w[1] = __builtin_amdgcn_cvt_pk_fp8_f32(b[2], b[3], w[1], true);
;             *(u32x2*)(base + bj * 128) = w; }
.LBB0_416:
	v_mov_b32_e32 v132, v200
	s_lshl_b32 s4, s4, 8
	v_readfirstlane_b32 s6, v132
	s_ashr_i32 s5, s6, 2
	s_andn2_b32 s5, s5, 63
	s_add_i32 s5, s5, s4
	v_and_or_b32 v136, v132, 15, s5
	v_ashrrev_i32_e32 v137, 31, v136
	v_lshl_add_u64 v[134:135], v[136:137], 2, s[28:29]
	global_load_dword v143, v[134:135], off
	v_lshlrev_b64 v[150:151], 12, v[136:137]
	v_mov_b32_e32 v144, v133
	v_mov_b32_e32 v145, v133
	s_lshl_b32 s4, s59, 8
	v_mov_b32_e32 v146, v133
	v_mov_b32_e32 v147, v133
	s_and_b32 s4, s4, 0xf00
	s_and_b32 s6, s6, 0xc0
	v_readlane_b32 s36, v254, 16
	v_readlane_b32 s34, v254, 38
	s_cmp_lt_i32 s59, 16
	v_readlane_b32 s38, v254, 18
	v_readlane_b32 s39, v254, 19
	v_readlane_b32 s35, v254, 39
	s_cselect_b32 s35, s39, s35
	s_cselect_b32 s34, s38, s34
	s_mov_b32 s5, s7
	s_sub_u32 s4, s4, 0x8000
	s_subb_u32 s5, s5, 0
	v_lshl_add_u64 v[150:151], s[34:35], 0, v[150:151]
	v_lshrrev_b32_e32 v132, 1, v132
	v_lshl_add_u64 v[150:151], v[150:151], 0, s[4:5]
	v_and_b32_e32 v132, 24, v132
	v_and_b32_e32 v210, 8, v200
	v_mov_b32_e32 v212, 0x8000
	v_lshl_or_b32 v132, v210, 2, v132
	v_xor_b32_e32 v210, 8, v210
	v_mov_b32_e32 v213, 0
	v_lshl_or_b32 v132, v210, 12, v132
	v_or_b32_e32 v148, 16, v136
	v_ashrrev_i32_e32 v149, 31, v148
	v_lshl_add_u64 v[152:153], v[148:149], 2, s[28:29]
	v_readlane_b32 s37, v254, 17
	s_waitcnt vmcnt(0)
	v_fmamk_f32 v137, v143, 0x3a000000, v142
	v_mul_f32_e32 v143, 0x4b800000, v137
	v_cmp_gt_f32_e32 vcc, s52, v137
	s_nop 1
	v_cndmask_b32_e32 v137, v137, v143, vcc
	v_rsq_f32_e32 v137, v137
	s_nop 0
	v_mul_f32_e32 v143, 0x45800000, v137
	v_cndmask_b32_e32 v137, v137, v143, vcc
	v_mul_f32_e32 v154, 0x3c800000, v137
	v_pk_mul_f32 v[124:125], v[124:125], v[154:155] op_sel_hi:[1,0]
	v_pk_mul_f32 v[120:121], v[120:121], v[154:155] op_sel_hi:[1,0]
	v_pk_mul_f32 v[116:117], v[116:117], v[154:155] op_sel_hi:[1,0]
	v_pk_mul_f32 v[112:113], v[112:113], v[154:155] op_sel_hi:[1,0]
	v_cvt_pk_fp8_f32 v144, v124, v125
	v_cvt_pk_fp8_f32 v145, v120, v121
	v_cvt_pk_fp8_f32 v146, v116, v117
	v_cvt_pk_fp8_f32 v147, v112, v113
	v_pk_mul_f32 v[126:127], v[126:127], v[154:155] op_sel_hi:[1,0]
	v_pk_mul_f32 v[122:123], v[122:123], v[154:155] op_sel_hi:[1,0]
	v_pk_mul_f32 v[118:119], v[118:119], v[154:155] op_sel_hi:[1,0]
	v_pk_mul_f32 v[114:115], v[114:115], v[154:155] op_sel_hi:[1,0]
	v_cvt_pk_fp8_f32 v144, v126, v127 op_sel:[0,0,1]
	v_cvt_pk_fp8_f32 v145, v122, v123 op_sel:[0,0,1]
	v_cvt_pk_fp8_f32 v146, v118, v119 op_sel:[0,0,1]
	v_cvt_pk_fp8_f32 v147, v114, v115 op_sel:[0,0,1]
	v_lshl_add_u64 v[112:113], v[150:151], 0, s[6:7]
	v_lshl_add_u64 v[112:113], v[112:113], 0, v[132:133]
	v_mov_b32_e32 v214, v144
	v_mov_b32_e32 v215, v145
	v_mov_b32_dpp v144, v146 row_ror:8 row_mask:0xf bank_mask:0xc
	v_mov_b32_dpp v145, v147 row_ror:8 row_mask:0xf bank_mask:0xc
	v_mov_b32_dpp v146, v214 row_ror:8 row_mask:0xf bank_mask:0x3
	v_mov_b32_dpp v147, v215 row_ror:8 row_mask:0xf bank_mask:0x3
	v_lshl_add_u64 v[216:217], v[112:113], 0, v[212:213]
	global_store_dwordx2 v[112:113], v[144:145], off
	global_store_dwordx2 v[216:217], v[146:147], off
	global_load_dword v122, v[152:153], off
	v_mov_b32_e32 v114, v133
	v_mov_b32_e32 v115, v133
	v_mov_b32_e32 v116, v133
	v_mov_b32_e32 v117, v133
	v_lshlrev_b64 v[120:121], 12, v[148:149]
	v_lshl_add_u64 v[120:121], s[34:35], 0, v[120:121]
	v_lshl_add_u64 v[120:121], v[120:121], 0, s[4:5]
	v_or_b32_e32 v118, 32, v136
	v_ashrrev_i32_e32 v119, 31, v118
	s_waitcnt vmcnt(0)
	v_fmamk_f32 v122, v122, 0x3a000000, v142
	v_mul_f32_e32 v123, 0x4b800000, v122
	v_cmp_gt_f32_e32 vcc, s52, v122
	s_nop 1
	v_cndmask_b32_e32 v122, v122, v123, vcc
	v_rsq_f32_e32 v124, v122
	v_lshl_add_u64 v[122:123], v[118:119], 2, s[28:29]
	v_mul_f32_e32 v125, 0x45800000, v124
	v_cndmask_b32_e32 v124, v124, v125, vcc
	v_mul_f32_e32 v124, 0x3c800000, v124
	v_pk_mul_f32 v[108:109], v[108:109], v[124:125] op_sel_hi:[1,0]
	v_pk_mul_f32 v[104:105], v[104:105], v[124:125] op_sel_hi:[1,0]
	v_pk_mul_f32 v[100:101], v[100:101], v[124:125] op_sel_hi:[1,0]
	v_pk_mul_f32 v[96:97], v[96:97], v[124:125] op_sel_hi:[1,0]
	v_cvt_pk_fp8_f32 v114, v108, v109
	v_cvt_pk_fp8_f32 v115, v104, v105
	v_cvt_pk_fp8_f32 v116, v100, v101
	v_cvt_pk_fp8_f32 v117, v96, v97
	v_pk_mul_f32 v[110:111], v[110:111], v[124:125] op_sel_hi:[1,0]
	v_pk_mul_f32 v[106:107], v[106:107], v[124:125] op_sel_hi:[1,0]
	v_pk_mul_f32 v[102:103], v[102:103], v[124:125] op_sel_hi:[1,0]
	v_pk_mul_f32 v[98:99], v[98:99], v[124:125] op_sel_hi:[1,0]
	v_cvt_pk_fp8_f32 v114, v110, v111 op_sel:[0,0,1]
	v_cvt_pk_fp8_f32 v115, v106, v107 op_sel:[0,0,1]
	v_cvt_pk_fp8_f32 v116, v102, v103 op_sel:[0,0,1]
	v_cvt_pk_fp8_f32 v117, v98, v99 op_sel:[0,0,1]
	v_lshl_add_u64 v[96:97], v[120:121], 0, s[6:7]
	v_lshl_add_u64 v[96:97], v[96:97], 0, v[132:133]
	v_mov_b32_e32 v214, v114
	v_mov_b32_e32 v215, v115
	v_mov_b32_dpp v114, v116 row_ror:8 row_mask:0xf bank_mask:0xc
	v_mov_b32_dpp v115, v117 row_ror:8 row_mask:0xf bank_mask:0xc
	v_mov_b32_dpp v116, v214 row_ror:8 row_mask:0xf bank_mask:0x3
	v_mov_b32_dpp v117, v215 row_ror:8 row_mask:0xf bank_mask:0x3
	v_lshl_add_u64 v[216:217], v[96:97], 0, v[212:213]
	global_store_dwordx2 v[96:97], v[114:115], off
	global_store_dwordx2 v[216:217], v[116:117], off
	global_load_dword v104, v[122:123], off
	v_mov_b32_e32 v96, v133
	v_mov_b32_e32 v97, v133
	v_mov_b32_e32 v98, v133
	v_mov_b32_e32 v99, v133
	v_lshlrev_b64 v[102:103], 12, v[118:119]
	v_lshl_add_u64 v[102:103], s[34:35], 0, v[102:103]
	v_lshl_add_u64 v[102:103], v[102:103], 0, s[4:5]
	v_or_b32_e32 v100, 48, v136
	v_ashrrev_i32_e32 v101, 31, v100
	s_waitcnt vmcnt(0)
;   __device__ __forceinline__ void operator()(const Acc& acc, const GUnit& u, int wr, int wc, int fr, int fq) const {
;     const int row0 = u.pm * 256 + wr * 64 + fr, pn = u.pn + pnoff;
; #pragma unroll
;     for (int ai = 0; ai < 2; ++ai)
; #pragma unroll
;       for (int m = 0; m < 4; ++m) {
;         const int row = row0 + ai * 128 + m * 16;
;         const float rs = rsqrtf(ss0[row] * (1.f / 2048.f) + EPS) * osc;
;         if (pn < 32) {
;           unsigned char* base = (unsigned char*)(pn < 16 ? q : z) + (size_t)row * 4096 + (pn & 15) * 256 + wc * 32 + 8 * fq;
; #pragma unroll
;           for (int bj = 0; bj < 2; ++bj) { const f32x4 a = acc[ai][bj][m][0] * rs, b = acc[ai][bj][m][1] * rs; u32x2 w;
;             w[0] = __builtin_amdgcn_cvt_pk_fp8_f32(a[0], a[1], 0, false); w[0] = __builtin_amdgcn_cvt_pk_fp8_f32(a[2], a[3], w[0], true);
;             w[1] = __builtin_amdgcn_cvt_pk_fp8_f32(b[0], b[1], 0, false); w[1] = __builtin_amdgcn_cvt_pk_fp8_f32(b[2], b[3], w[1], true);
;             *(u32x2*)(base + bj * 128) = w; }
	v_fmamk_f32 v104, v104, 0x3a000000, v142
	v_mul_f32_e32 v105, 0x4b800000, v104
	v_cmp_gt_f32_e32 vcc, s52, v104
	s_nop 1
	v_cndmask_b32_e32 v104, v104, v105, vcc
	v_rsq_f32_e32 v106, v104
	v_lshl_add_u64 v[104:105], v[100:101], 2, s[28:29]
	v_mul_f32_e32 v107, 0x45800000, v106
	v_cndmask_b32_e32 v106, v106, v107, vcc
	v_mul_f32_e32 v106, 0x3c800000, v106
	v_pk_mul_f32 v[92:93], v[92:93], v[106:107] op_sel_hi:[1,0]
	v_pk_mul_f32 v[88:89], v[88:89], v[106:107] op_sel_hi:[1,0]
	v_pk_mul_f32 v[84:85], v[84:85], v[106:107] op_sel_hi:[1,0]
	v_pk_mul_f32 v[80:81], v[80:81], v[106:107] op_sel_hi:[1,0]
	v_cvt_pk_fp8_f32 v96, v92, v93
	v_cvt_pk_fp8_f32 v97, v88, v89
	v_cvt_pk_fp8_f32 v98, v84, v85
	v_cvt_pk_fp8_f32 v99, v80, v81
	v_pk_mul_f32 v[94:95], v[94:95], v[106:107] op_sel_hi:[1,0]
	v_pk_mul_f32 v[90:91], v[90:91], v[106:107] op_sel_hi:[1,0]
	v_pk_mul_f32 v[86:87], v[86:87], v[106:107] op_sel_hi:[1,0]
	v_pk_mul_f32 v[82:83], v[82:83], v[106:107] op_sel_hi:[1,0]
	v_cvt_pk_fp8_f32 v96, v94, v95 op_sel:[0,0,1]
	v_cvt_pk_fp8_f32 v97, v90, v91 op_sel:[0,0,1]
	v_cvt_pk_fp8_f32 v98, v86, v87 op_sel:[0,0,1]
	v_cvt_pk_fp8_f32 v99, v82, v83 op_sel:[0,0,1]
	v_lshl_add_u64 v[80:81], v[102:103], 0, s[6:7]
	v_lshl_add_u64 v[80:81], v[80:81], 0, v[132:133]
	v_mov_b32_e32 v214, v96
	v_mov_b32_e32 v215, v97
	v_mov_b32_dpp v96, v98 row_ror:8 row_mask:0xf bank_mask:0xc
	v_mov_b32_dpp v97, v99 row_ror:8 row_mask:0xf bank_mask:0xc
	v_mov_b32_dpp v98, v214 row_ror:8 row_mask:0xf bank_mask:0x3
	v_mov_b32_dpp v99, v215 row_ror:8 row_mask:0xf bank_mask:0x3
	v_lshl_add_u64 v[216:217], v[80:81], 0, v[212:213]
	global_store_dwordx2 v[80:81], v[96:97], off
	global_store_dwordx2 v[216:217], v[98:99], off
	global_load_dword v84, v[104:105], off
	v_mov_b32_e32 v80, v133
	v_mov_b32_e32 v81, v133
	v_mov_b32_e32 v82, v133
	v_mov_b32_e32 v83, v133
	s_waitcnt vmcnt(0)
	v_fmamk_f32 v84, v84, 0x3a000000, v142
	v_mul_f32_e32 v85, 0x4b800000, v84
	v_cmp_gt_f32_e32 vcc, s52, v84
	s_nop 1
	v_cndmask_b32_e32 v84, v84, v85, vcc
	v_rsq_f32_e32 v86, v84
	v_lshlrev_b64 v[84:85], 12, v[100:101]
	v_lshl_add_u64 v[84:85], s[34:35], 0, v[84:85]
	v_lshl_add_u64 v[84:85], v[84:85], 0, s[4:5]
	v_mul_f32_e32 v87, 0x45800000, v86
	v_cndmask_b32_e32 v86, v86, v87, vcc
	v_mul_f32_e32 v86, 0x3c800000, v86
	v_pk_mul_f32 v[76:77], v[76:77], v[86:87] op_sel_hi:[1,0]
	v_pk_mul_f32 v[72:73], v[72:73], v[86:87] op_sel_hi:[1,0]
	v_pk_mul_f32 v[68:69], v[68:69], v[86:87] op_sel_hi:[1,0]
	v_pk_mul_f32 v[64:65], v[64:65], v[86:87] op_sel_hi:[1,0]
	v_cvt_pk_fp8_f32 v80, v76, v77
	v_cvt_pk_fp8_f32 v81, v72, v73
	v_cvt_pk_fp8_f32 v82, v68, v69
	v_cvt_pk_fp8_f32 v83, v64, v65
	v_pk_mul_f32 v[78:79], v[78:79], v[86:87] op_sel_hi:[1,0]
	v_pk_mul_f32 v[74:75], v[74:75], v[86:87] op_sel_hi:[1,0]
	v_pk_mul_f32 v[70:71], v[70:71], v[86:87] op_sel_hi:[1,0]
	v_pk_mul_f32 v[66:67], v[66:67], v[86:87] op_sel_hi:[1,0]
	v_cvt_pk_fp8_f32 v80, v78, v79 op_sel:[0,0,1]
	v_cvt_pk_fp8_f32 v81, v74, v75 op_sel:[0,0,1]
	v_cvt_pk_fp8_f32 v82, v70, v71 op_sel:[0,0,1]
	v_cvt_pk_fp8_f32 v83, v66, v67 op_sel:[0,0,1]
	v_lshl_add_u64 v[64:65], v[84:85], 0, s[6:7]
	v_lshl_add_u64 v[64:65], v[64:65], 0, v[132:133]
	v_mov_b32_e32 v214, v80
	v_mov_b32_e32 v215, v81
	v_mov_b32_dpp v80, v82 row_ror:8 row_mask:0xf bank_mask:0xc
	v_mov_b32_dpp v81, v83 row_ror:8 row_mask:0xf bank_mask:0xc
	v_mov_b32_dpp v82, v214 row_ror:8 row_mask:0xf bank_mask:0x3
	v_mov_b32_dpp v83, v215 row_ror:8 row_mask:0xf bank_mask:0x3
	v_lshl_add_u64 v[216:217], v[64:65], 0, v[212:213]
	global_store_dwordx2 v[64:65], v[80:81], off
	global_store_dwordx2 v[216:217], v[82:83], off
	global_load_dword v66, v[134:135], off offset:512
	v_mov_b32_e32 v64, v133
	v_mov_b32_e32 v65, v133
	v_lshl_add_u64 v[68:69], v[112:113], 0, s[12:13]
	s_waitcnt vmcnt(0)
	v_fmamk_f32 v66, v66, 0x3a000000, v142
	v_mul_f32_e32 v67, 0x4b800000, v66
	v_cmp_gt_f32_e32 vcc, s52, v66
	s_nop 1
	v_cndmask_b32_e32 v66, v66, v67, vcc
	v_rsq_f32_e32 v70, v66
	v_mov_b32_e32 v66, v133
	v_mov_b32_e32 v67, v133
	v_mul_f32_e32 v71, 0x45800000, v70
	v_cndmask_b32_e32 v70, v70, v71, vcc
	v_mul_f32_e32 v70, 0x3c800000, v70
	v_pk_mul_f32 v[60:61], v[60:61], v[70:71] op_sel_hi:[1,0]
	v_pk_mul_f32 v[56:57], v[56:57], v[70:71] op_sel_hi:[1,0]
	v_pk_mul_f32 v[52:53], v[52:53], v[70:71] op_sel_hi:[1,0]
	v_pk_mul_f32 v[48:49], v[48:49], v[70:71] op_sel_hi:[1,0]
	v_cvt_pk_fp8_f32 v64, v60, v61
	v_cvt_pk_fp8_f32 v65, v56, v57
	v_cvt_pk_fp8_f32 v66, v52, v53
	v_cvt_pk_fp8_f32 v67, v48, v49
	v_pk_mul_f32 v[62:63], v[62:63], v[70:71] op_sel_hi:[1,0]
	v_pk_mul_f32 v[58:59], v[58:59], v[70:71] op_sel_hi:[1,0]
	v_pk_mul_f32 v[54:55], v[54:55], v[70:71] op_sel_hi:[1,0]
	v_pk_mul_f32 v[50:51], v[50:51], v[70:71] op_sel_hi:[1,0]
	v_cvt_pk_fp8_f32 v64, v62, v63 op_sel:[0,0,1]
	v_cvt_pk_fp8_f32 v65, v58, v59 op_sel:[0,0,1]
	v_cvt_pk_fp8_f32 v66, v54, v55 op_sel:[0,0,1]
	v_cvt_pk_fp8_f32 v67, v50, v51 op_sel:[0,0,1]
	v_add_co_u32_e32 v48, vcc, s53, v112
	v_lshl_add_u64 v[52:53], v[112:113], 0, s[14:15]
	s_nop 0
	v_addc_co_u32_e32 v49, vcc, 0, v113, vcc
	v_mov_b32_e32 v214, v64
	v_mov_b32_e32 v215, v65
	v_mov_b32_dpp v64, v66 row_ror:8 row_mask:0xf bank_mask:0xc
	v_mov_b32_dpp v65, v67 row_ror:8 row_mask:0xf bank_mask:0xc
	v_mov_b32_dpp v66, v214 row_ror:8 row_mask:0xf bank_mask:0x3
	v_mov_b32_dpp v67, v215 row_ror:8 row_mask:0xf bank_mask:0x3
	v_lshl_add_u64 v[216:217], v[48:49], 0, v[212:213]
	global_store_dwordx2 v[48:49], v[64:65], off
	global_store_dwordx2 v[216:217], v[66:67], off
	global_load_dword v50, v[134:135], off offset:576
	v_mov_b32_e32 v48, v133
	v_mov_b32_e32 v49, v133
	s_waitcnt vmcnt(0)
;   __device__ __forceinline__ void operator()(const Acc& acc, const GUnit& u, int wr, int wc, int fr, int fq) const {
;     const int row0 = u.pm * 256 + wr * 64 + fr, pn = u.pn + pnoff;
; #pragma unroll
;     for (int ai = 0; ai < 2; ++ai)
; #pragma unroll
;       for (int m = 0; m < 4; ++m) {
;         const int row = row0 + ai * 128 + m * 16;
;         const float rs = rsqrtf(ss0[row] * (1.f / 2048.f) + EPS) * osc;
;         if (pn < 32) {
;           unsigned char* base = (unsigned char*)(pn < 16 ? q : z) + (size_t)row * 4096 + (pn & 15) * 256 + wc * 32 + 8 * fq;
; #pragma unroll
;           for (int bj = 0; bj < 2; ++bj) { const f32x4 a = acc[ai][bj][m][0] * rs, b = acc[ai][bj][m][1] * rs; u32x2 w;
;             w[0] = __builtin_amdgcn_cvt_pk_fp8_f32(a[0], a[1], 0, false); w[0] = __builtin_amdgcn_cvt_pk_fp8_f32(a[2], a[3], w[0], true);
;             w[1] = __builtin_amdgcn_cvt_pk_fp8_f32(b[0], b[1], 0, false); w[1] = __builtin_amdgcn_cvt_pk_fp8_f32(b[2], b[3], w[1], true);
;             *(u32x2*)(base + bj * 128) = w; }
	v_fmamk_f32 v50, v50, 0x3a000000, v142
	v_mul_f32_e32 v51, 0x4b800000, v50
	v_cmp_gt_f32_e32 vcc, s52, v50
	s_nop 1
	v_cndmask_b32_e32 v50, v50, v51, vcc
	v_rsq_f32_e32 v54, v50
	v_mov_b32_e32 v50, v133
	v_mov_b32_e32 v51, v133
	v_mul_f32_e32 v55, 0x45800000, v54
	v_cndmask_b32_e32 v54, v54, v55, vcc
	v_mul_f32_e32 v54, 0x3c800000, v54
	v_pk_mul_f32 v[44:45], v[44:45], v[54:55] op_sel_hi:[1,0]
	v_pk_mul_f32 v[40:41], v[40:41], v[54:55] op_sel_hi:[1,0]
	v_pk_mul_f32 v[36:37], v[36:37], v[54:55] op_sel_hi:[1,0]
	v_pk_mul_f32 v[32:33], v[32:33], v[54:55] op_sel_hi:[1,0]
	v_cvt_pk_fp8_f32 v48, v44, v45
	v_cvt_pk_fp8_f32 v49, v40, v41
	v_cvt_pk_fp8_f32 v50, v36, v37
	v_cvt_pk_fp8_f32 v51, v32, v33
	v_pk_mul_f32 v[46:47], v[46:47], v[54:55] op_sel_hi:[1,0]
	v_pk_mul_f32 v[42:43], v[42:43], v[54:55] op_sel_hi:[1,0]
	v_pk_mul_f32 v[38:39], v[38:39], v[54:55] op_sel_hi:[1,0]
	v_pk_mul_f32 v[34:35], v[34:35], v[54:55] op_sel_hi:[1,0]
	v_cvt_pk_fp8_f32 v48, v46, v47 op_sel:[0,0,1]
	v_cvt_pk_fp8_f32 v49, v42, v43 op_sel:[0,0,1]
	v_cvt_pk_fp8_f32 v50, v38, v39 op_sel:[0,0,1]
	v_cvt_pk_fp8_f32 v51, v34, v35 op_sel:[0,0,1]
	v_add_co_u32_e32 v32, vcc, s54, v112
	v_lshl_add_u64 v[36:37], v[112:113], 0, s[16:17]
	s_nop 0
	v_addc_co_u32_e32 v33, vcc, 0, v113, vcc
	v_mov_b32_e32 v214, v48
	v_mov_b32_e32 v215, v49
	v_mov_b32_dpp v48, v50 row_ror:8 row_mask:0xf bank_mask:0xc
	v_mov_b32_dpp v49, v51 row_ror:8 row_mask:0xf bank_mask:0xc
	v_mov_b32_dpp v50, v214 row_ror:8 row_mask:0xf bank_mask:0x3
	v_mov_b32_dpp v51, v215 row_ror:8 row_mask:0xf bank_mask:0x3
	v_lshl_add_u64 v[216:217], v[32:33], 0, v[212:213]
	global_store_dwordx2 v[32:33], v[48:49], off
	global_store_dwordx2 v[216:217], v[50:51], off
	global_load_dword v34, v[134:135], off offset:640
	v_mov_b32_e32 v32, v133
	v_mov_b32_e32 v33, v133
	s_waitcnt vmcnt(0)
	v_fmamk_f32 v34, v34, 0x3a000000, v142
	v_mul_f32_e32 v35, 0x4b800000, v34
	v_cmp_gt_f32_e32 vcc, s52, v34
	s_nop 1
	v_cndmask_b32_e32 v34, v34, v35, vcc
	v_rsq_f32_e32 v38, v34
	v_mov_b32_e32 v34, v133
	v_mov_b32_e32 v35, v133
	v_mul_f32_e32 v39, 0x45800000, v38
	v_cndmask_b32_e32 v38, v38, v39, vcc
	v_mul_f32_e32 v38, 0x3c800000, v38
	v_pk_mul_f32 v[28:29], v[28:29], v[38:39] op_sel_hi:[1,0]
	v_pk_mul_f32 v[24:25], v[24:25], v[38:39] op_sel_hi:[1,0]
	v_pk_mul_f32 v[20:21], v[20:21], v[38:39] op_sel_hi:[1,0]
	v_pk_mul_f32 v[16:17], v[16:17], v[38:39] op_sel_hi:[1,0]
	v_cvt_pk_fp8_f32 v32, v28, v29
	v_cvt_pk_fp8_f32 v33, v24, v25
	v_cvt_pk_fp8_f32 v34, v20, v21
	v_cvt_pk_fp8_f32 v35, v16, v17
	v_pk_mul_f32 v[30:31], v[30:31], v[38:39] op_sel_hi:[1,0]
	v_pk_mul_f32 v[26:27], v[26:27], v[38:39] op_sel_hi:[1,0]
	v_pk_mul_f32 v[22:23], v[22:23], v[38:39] op_sel_hi:[1,0]
	v_pk_mul_f32 v[18:19], v[18:19], v[38:39] op_sel_hi:[1,0]
	v_cvt_pk_fp8_f32 v32, v30, v31 op_sel:[0,0,1]
	v_cvt_pk_fp8_f32 v33, v26, v27 op_sel:[0,0,1]
	v_cvt_pk_fp8_f32 v34, v22, v23 op_sel:[0,0,1]
	v_cvt_pk_fp8_f32 v35, v18, v19 op_sel:[0,0,1]
	v_add_co_u32_e32 v16, vcc, s55, v112
	v_mov_b32_e32 v18, v133
	s_nop 0
	v_addc_co_u32_e32 v17, vcc, 0, v113, vcc
	v_mov_b32_e32 v214, v32
	v_mov_b32_e32 v215, v33
	v_mov_b32_dpp v32, v34 row_ror:8 row_mask:0xf bank_mask:0xc
	v_mov_b32_dpp v33, v35 row_ror:8 row_mask:0xf bank_mask:0xc
	v_mov_b32_dpp v34, v214 row_ror:8 row_mask:0xf bank_mask:0x3
	v_mov_b32_dpp v35, v215 row_ror:8 row_mask:0xf bank_mask:0x3
	v_lshl_add_u64 v[216:217], v[16:17], 0, v[212:213]
	global_store_dwordx2 v[16:17], v[32:33], off
	global_store_dwordx2 v[216:217], v[34:35], off
	global_load_dword v20, v[134:135], off offset:704
	v_mov_b32_e32 v16, v133
	v_mov_b32_e32 v17, v133
	v_mov_b32_e32 v19, v133
	s_andn2_b64 vcc, exec, s[30:31]
	s_waitcnt vmcnt(0)
	v_fmamk_f32 v20, v20, 0x3a000000, v142
	v_mul_f32_e32 v21, 0x4b800000, v20
	v_cmp_gt_f32_e64 s[4:5], s52, v20
	s_nop 1
	v_cndmask_b32_e64 v20, v20, v21, s[4:5]
	v_rsq_f32_e32 v22, v20
	v_lshl_add_u64 v[20:21], v[112:113], 0, s[20:21]
	v_mul_f32_e32 v23, 0x45800000, v22
	v_cndmask_b32_e64 v22, v22, v23, s[4:5]
	v_mul_f32_e32 v22, 0x3c800000, v22
	v_pk_mul_f32 v[12:13], v[12:13], v[22:23] op_sel_hi:[1,0]
	v_pk_mul_f32 v[8:9], v[8:9], v[22:23] op_sel_hi:[1,0]
	v_pk_mul_f32 v[4:5], v[4:5], v[22:23] op_sel_hi:[1,0]
	v_pk_mul_f32 v[0:1], v[0:1], v[22:23] op_sel_hi:[1,0]
	v_cvt_pk_fp8_f32 v16, v12, v13
	v_cvt_pk_fp8_f32 v17, v8, v9
	v_cvt_pk_fp8_f32 v18, v4, v5
	v_cvt_pk_fp8_f32 v19, v0, v1
	v_pk_mul_f32 v[14:15], v[14:15], v[22:23] op_sel_hi:[1,0]
	v_pk_mul_f32 v[10:11], v[10:11], v[22:23] op_sel_hi:[1,0]
	v_pk_mul_f32 v[6:7], v[6:7], v[22:23] op_sel_hi:[1,0]
	v_pk_mul_f32 v[2:3], v[2:3], v[22:23] op_sel_hi:[1,0]
	v_cvt_pk_fp8_f32 v16, v14, v15 op_sel:[0,0,1]
	v_cvt_pk_fp8_f32 v17, v10, v11 op_sel:[0,0,1]
	v_cvt_pk_fp8_f32 v18, v6, v7 op_sel:[0,0,1]
	v_cvt_pk_fp8_f32 v19, v2, v3 op_sel:[0,0,1]
	v_add_co_u32_e64 v0, s[4:5], s56, v112
	s_nop 1
	v_addc_co_u32_e64 v1, s[4:5], 0, v113, s[4:5]
	s_mov_b64 s[4:5], -1
	v_mov_b32_e32 v214, v16
	v_mov_b32_e32 v215, v17
	v_mov_b32_dpp v16, v18 row_ror:8 row_mask:0xf bank_mask:0xc
	v_mov_b32_dpp v17, v19 row_ror:8 row_mask:0xf bank_mask:0xc
	v_mov_b32_dpp v18, v214 row_ror:8 row_mask:0xf bank_mask:0x3
	v_mov_b32_dpp v19, v215 row_ror:8 row_mask:0xf bank_mask:0x3
	v_lshl_add_u64 v[216:217], v[0:1], 0, v[212:213]
	global_store_dwordx2 v[0:1], v[16:17], off
	global_store_dwordx2 v[216:217], v[18:19], off
	s_cbranch_vccnz .LBB0_405
	s_andn2_b64 vcc, exec, s[8:9]
	s_cbranch_vccnz .LBB0_404
	s_barrier
	s_branch .LBB0_404

; #define G8_STAGE(bufoff, gbase, NM) do { _Pragma("unroll") for (int _i = 0; _i < 2; ++_i) { \
;     const char* _b = (const char*)(gbase) + (_i ? p2##NM : (size_t)0); asm volatile("" : "+s"(_b));     \
;     __builtin_amdgcn_global_load_lds((const unsigned*)(_b + voff##NM), (LAS unsigned*)(lds + (bufoff) + ldsw + _i * 8192), 16, 0, 0); } } while (0)
; #define G8_WAIT_V(n) asm volatile("s_waitcnt vmcnt(" #n ")" ::: "memory")
; #define G8_BAR __builtin_amdgcn_s_barrier()
;     ...
;   const unsigned ldsw = (unsigned)wid * 1024u;
;   const int aoff = lds_byte(wr * 64 + fr, fq * 8), boff = lds_byte(wc * 32 + fr, fq * 8);
;     ...
;   G8_STAGE(G8_SB(0, 0), cB, B); G8_STAGE(G8_SB(0, 1), cB + hstepB, B); G8_STAGE(G8_SA(0, 0), cA, A); G8_STAGE(G8_SA(0, 1), cA + hstepA, A);
;   if (wr == 1) G8_BAR;
;   G8_WAIT_V(2); G8_BAR;
;   G8_STAGE(G8_SB(1, 0), cB + kstep, B); G8_STAGE(G8_SA(1, 0), cA + kstep, A); G8_STAGE(G8_SB(1, 1), cB + hstepB + kstep, B);
;   G8_WAIT_V(6); G8_BAR;
.LBB0_952:
	s_lshl_b32 s13, s13, 13
	s_ashr_i32 s34, s16, 1
	s_lshl_b32 s14, s14, 13
	s_and_b32 s13, s13, 0x6000
	s_add_u32 s16, s4, 0x80
	s_addc_u32 s17, s5, 0
	s_waitcnt vmcnt(2)
	s_barrier
	s_add_i32 s47, s0, 0x18000
	s_mov_b32 m0, s47
	v_lshl_add_u64 v[2:3], s[16:17], 0, v[198:199]
	s_add_u32 s16, s4, 0x4080
	s_addc_u32 s17, s5, 0
	global_load_lds_dwordx4 v[2:3], off
	s_add_i32 s48, s0, 0x1a000
	v_lshl_add_u64 v[2:3], s[16:17], 0, v[198:199]
	s_add_u32 s16, s8, 0x80
	s_mov_b32 m0, s48
	s_addc_u32 s17, s9, 0
	global_load_lds_dwordx4 v[2:3], off
	s_add_i32 s49, s0, 0x8000
	v_lshl_add_u64 v[2:3], s[16:17], 0, v[196:197]
	s_add_u32 s16, s8, 0x40080
	s_mov_b32 m0, s49
	s_addc_u32 s17, s9, 0
	global_load_lds_dwordx4 v[2:3], off
	s_add_i32 s50, s0, 0xa000
	v_lshl_add_u64 v[2:3], s[16:17], 0, v[196:197]
	s_add_u32 s16, s4, 0x8080
	s_mov_b32 m0, s50
	s_addc_u32 s17, s5, 0
	global_load_lds_dwordx4 v[2:3], off
	s_add_i32 s51, s0, 0x1c000
	s_mov_b32 m0, s51
	v_lshl_add_u64 v[2:3], s[16:17], 0, v[198:199]
	s_add_u32 s16, s4, 0xc080
	s_addc_u32 s17, s5, 0
	s_add_i32 s52, s0, 0x1e000
	global_load_lds_dwordx4 v[2:3], off
	s_mov_b32 m0, s52
	v_lshl_add_u64 v[2:3], s[16:17], 0, v[198:199]
	global_load_lds_dwordx4 v[2:3], off
	v_and_b32_e32 v1, 15, v0
	v_and_b32_e32 v2, 48, v0
	v_lshlrev_b32_e32 v0, 2, v0
	v_lshlrev_b32_e32 v1, 6, v1
	v_and_b32_e32 v0, 32, v0
	v_or_b32_e32 v3, v1, v2
	v_bitop3_b32 v1, v1, v0, v2 bitop3:0x36
	v_or_b32_e32 v1, s13, v1
	s_waitcnt vmcnt(6)
	v_bitop3_b32 v0, v3, s14, v0 bitop3:0xde
	s_cmpk_lt_u32 s12, 0x100
	v_add_u32_e32 v201, 0, v1
	s_cselect_b64 s[12:13], -1, 0
	s_add_i32 s53, s88, s89
	v_add_u32_e32 v202, 0x10000, v201
	v_add_u32_e32 v203, 0x1000, v202
	v_add_u32_e32 v204, 0, v0
	s_mov_b32 s14, 0x3d800000
	s_mov_b64 s[16:17], 0x100000
	s_mov_b32 s54, 0x100000
	s_mov_b64 s[18:19], 0x120000
	s_mov_b32 s55, 0x120000
	s_mov_b64 s[20:21], 0x140000
	s_mov_b32 s56, 0x140000
	s_mov_b64 s[22:23], 0x160000
	s_mov_b32 s57, 0x160000
	s_mov_b64 s[28:29], s[8:9]
	s_barrier
	s_branch .LBB0_955

; #define G8_STAGE(bufoff, gbase, NM) do { _Pragma("unroll") for (int _i = 0; _i < 2; ++_i) { \
;     const char* _b = (const char*)(gbase) + (_i ? p2##NM : (size_t)0); asm volatile("" : "+s"(_b));     \
;     __builtin_amdgcn_global_load_lds((const unsigned*)(_b + voff##NM), (LAS unsigned*)(lds + (bufoff) + ldsw + _i * 8192), 16, 0, 0); } } while (0)
; #define G8_WAIT_V(n) asm volatile("s_waitcnt vmcnt(" #n ")" ::: "memory")
; #define G8_WAIT_L(n) asm volatile("s_waitcnt lgkmcnt(" #n ")" ::: "memory")
; #define G8_BAR __builtin_amdgcn_s_barrier()
; #define G8_SCHED __builtin_amdgcn_sched_barrier(0)
;     ...
;       G8_LDB(B0, 1, 0); G8_LDB(B1, 1, 1); G8_SCHED; G8_LDA(At, 1, 0); G8_STAGE(G8_SA(0, 1), a2 + hstepA, A);
;       G8_WAIT_V(8); G8_WAIT_L(0); G8_BAR; if (d0b) G8_MMA(0, 0, At, B0); if (d1b) G8_MMA(0, 1, At, B1); G8_BAR; G8_SCHED;
.LBB0_966:
	s_barrier
	v_add_u32_e32 v12, 0x18000, v201
	v_add_u32_e32 v28, 0x1000, v12
	ds_read_b128 v[0:3], v12
	ds_read_b128 v[4:7], v12 offset:1024
	ds_read_b128 v[8:11], v12 offset:2048
	ds_read_b128 v[12:15], v12 offset:3072
	ds_read_b128 v[16:19], v28
	ds_read_b128 v[20:23], v28 offset:1024
	ds_read_b128 v[24:27], v28 offset:2048
	ds_read_b128 v[28:31], v28 offset:3072
	s_add_u32 s42, s8, 0x80000
	s_addc_u32 s43, s9, 0
	s_add_u32 s8, s8, 0xc0000
	s_mov_b32 m0, s33
	s_waitcnt lgkmcnt(0)
	ds_read_b128 v[32:35], v204 offset:32768
	ds_read_b128 v[36:39], v204 offset:33792
	ds_read_b128 v[40:43], v204 offset:34816
	ds_read_b128 v[44:47], v204 offset:35840
	ds_read_b128 v[48:51], v204 offset:36864
	ds_read_b128 v[52:55], v204 offset:37888
	ds_read_b128 v[56:59], v204 offset:38912
	ds_read_b128 v[60:63], v204 offset:39936
	s_addc_u32 s9, s9, 0
	v_lshl_add_u64 v[66:67], s[42:43], 0, v[196:197]
	global_load_lds_dwordx4 v[66:67], off
	s_mov_b32 m0, s46
	v_lshl_add_u64 v[66:67], s[8:9], 0, v[196:197]
	global_load_lds_dwordx4 v[66:67], off
	s_waitcnt vmcnt(8)
	s_waitcnt lgkmcnt(0)
	v_cndmask_b32_e64 v64, 0, 1, s[40:41]
	v_cmp_ne_u32_e64 s[8:9], 1, v64
	s_andn2_b64 vcc, exec, s[40:41]
	s_barrier
	s_cbranch_vccnz .LBB0_968
	s_setprio 1
	s_waitcnt lgkmcnt(0)
	v_mfma_f32_16x16x128_f8f6f4 v[192:195], v[0:7], v[32:39], v[192:195]
	v_mfma_f32_16x16x128_f8f6f4 v[188:191], v[8:15], v[32:39], v[188:191]
	v_mfma_f32_16x16x128_f8f6f4 v[160:163], v[0:7], v[40:47], v[160:163]
	v_mfma_f32_16x16x128_f8f6f4 v[156:159], v[8:15], v[40:47], v[156:159]
	v_mfma_f32_16x16x128_f8f6f4 v[128:131], v[0:7], v[48:55], v[128:131]
	v_mfma_f32_16x16x128_f8f6f4 v[124:127], v[8:15], v[48:55], v[124:127]
	v_mfma_f32_16x16x128_f8f6f4 v[96:99], v[0:7], v[56:63], v[96:99]
	v_mfma_f32_16x16x128_f8f6f4 v[92:95], v[8:15], v[56:63], v[92:95]
	s_setprio 0
	s_setprio 1
	v_mfma_f32_16x16x128_f8f6f4 v[184:187], v[16:23], v[32:39], v[184:187]
	v_mfma_f32_16x16x128_f8f6f4 v[180:183], v[24:31], v[32:39], v[180:183]
	v_mfma_f32_16x16x128_f8f6f4 v[152:155], v[16:23], v[40:47], v[152:155]
	v_mfma_f32_16x16x128_f8f6f4 v[148:151], v[24:31], v[40:47], v[148:151]
	v_mfma_f32_16x16x128_f8f6f4 v[120:123], v[16:23], v[48:55], v[120:123]
	v_mfma_f32_16x16x128_f8f6f4 v[116:119], v[24:31], v[48:55], v[116:119]
	v_mfma_f32_16x16x128_f8f6f4 v[88:91], v[16:23], v[56:63], v[88:91]
	v_mfma_f32_16x16x128_f8f6f4 v[84:87], v[24:31], v[56:63], v[84:87]
	s_setprio 0

;   __device__ __forceinline__ void operator()(const Acc& acc, const GUnit& u, int wr, int wc, int fr, int fq) const {
;     const int row0 = u.pm * 256 + wr * 64 + fr;
;     unsigned char* ob = Q0 + (size_t)u.pn * 256 + wc * 32 + 8 * fq;
; #pragma unroll
;     for (int ai = 0; ai < 2; ++ai)
; #pragma unroll
;       for (int m = 0; m < 4; ++m) {
;         const int row = row0 + ai * 128 + m * 16;
; #pragma unroll
;         for (int bj = 0; bj < 2; ++bj) { const f32x4 a = acc[ai][bj][m][0] * osc, b = acc[ai][bj][m][1] * osc; u32x2 w;
;           w[0] = __builtin_amdgcn_cvt_pk_fp8_f32(a[0], a[1], 0, false); w[0] = __builtin_amdgcn_cvt_pk_fp8_f32(a[2], a[3], w[0], true);
;           w[1] = __builtin_amdgcn_cvt_pk_fp8_f32(b[0], b[1], 0, false); w[1] = __builtin_amdgcn_cvt_pk_fp8_f32(b[2], b[3], w[1], true);
;           *(u32x2*)(ob + (size_t)row * 8192 + bj * 128) = w; }
;       }
.LBB0_972:
	v_mov_b32_e32 v0, v200
	s_lshl_b32 s8, s30, 8
	v_readfirstlane_b32 s27, v0
	s_ashr_i32 s9, s27, 2
	s_andn2_b32 s9, s9, 63
	s_add_i32 s9, s9, s8
	v_and_or_b32 v2, v0, 15, s9
	v_lshrrev_b32_e32 v0, 1, v0
	v_and_b32_e32 v64, 24, v0
	v_and_b32_e32 v210, 8, v200
	v_mov_b32_e32 v212, 0x10000
	v_lshl_or_b32 v64, v210, 2, v64
	v_xor_b32_e32 v210, 8, v210
	v_mov_b32_e32 v213, 0
	v_lshl_or_b32 v64, v210, 13, v64
	v_pk_mul_f32 v[0:1], v[192:193], s[14:15] op_sel_hi:[1,0]
	v_pk_mul_f32 v[6:7], v[188:189], s[14:15] op_sel_hi:[1,0]
	v_mov_b32_e32 v8, v65
	v_mov_b32_e32 v9, v65
	v_cvt_pk_fp8_f32 v8, v0, v1
	v_cvt_pk_fp8_f32 v9, v6, v7
	s_ashr_i32 s35, s34, 31
	v_pk_mul_f32 v[0:1], v[194:195], s[14:15] op_sel_hi:[1,0]
	v_pk_mul_f32 v[6:7], v[190:191], s[14:15] op_sel_hi:[1,0]
	s_lshl_b64 s[8:9], s[34:35], 8
	v_cvt_pk_fp8_f32 v8, v0, v1 op_sel:[0,0,1]
	v_cvt_pk_fp8_f32 v9, v6, v7 op_sel:[0,0,1]
	v_pk_mul_f32 v[0:1], v[184:185], s[14:15] op_sel_hi:[1,0]
	v_pk_mul_f32 v[6:7], v[180:181], s[14:15] op_sel_hi:[1,0]
	v_mov_b32_e32 v10, v65
	v_mov_b32_e32 v11, v65
	s_add_u32 s8, s92, s8
	v_cvt_pk_fp8_f32 v10, v0, v1
	v_cvt_pk_fp8_f32 v11, v6, v7
	s_addc_u32 s9, s93, s9
	s_and_b32 s27, s27, 0xc0
	s_add_u32 s8, s8, s27
	v_pk_mul_f32 v[0:1], v[186:187], s[14:15] op_sel_hi:[1,0]
	v_pk_mul_f32 v[6:7], v[182:183], s[14:15] op_sel_hi:[1,0]
	s_addc_u32 s9, s9, 0
	s_sub_u32 s8, s8, 0x10000
	s_subb_u32 s9, s9, 0
	v_ashrrev_i32_e32 v3, 31, v2
	v_cvt_pk_fp8_f32 v10, v0, v1 op_sel:[0,0,1]
	v_cvt_pk_fp8_f32 v11, v6, v7 op_sel:[0,0,1]
	v_lshl_add_u64 v[4:5], s[8:9], 0, v[64:65]
	v_lshlrev_b64 v[0:1], 13, v[2:3]
	v_lshl_add_u64 v[0:1], v[4:5], 0, v[0:1]
	v_mov_b32_e32 v214, v8
	v_mov_b32_e32 v215, v9
	v_mov_b32_dpp v8, v10 row_ror:8 row_mask:0xf bank_mask:0xc
	v_mov_b32_dpp v9, v11 row_ror:8 row_mask:0xf bank_mask:0xc
	v_mov_b32_dpp v10, v214 row_ror:8 row_mask:0xf bank_mask:0x3
	v_mov_b32_dpp v11, v215 row_ror:8 row_mask:0xf bank_mask:0x3
	v_lshl_add_u64 v[216:217], v[0:1], 0, v[212:213]
	global_store_dwordx2 v[0:1], v[8:9], off
	global_store_dwordx2 v[216:217], v[10:11], off
	v_pk_mul_f32 v[8:9], v[160:161], s[14:15] op_sel_hi:[1,0]
	v_pk_mul_f32 v[10:11], v[156:157], s[14:15] op_sel_hi:[1,0]
	v_mov_b32_e32 v12, v65
	v_mov_b32_e32 v13, v65
	v_cvt_pk_fp8_f32 v12, v8, v9
	v_cvt_pk_fp8_f32 v13, v10, v11
	v_pk_mul_f32 v[8:9], v[162:163], s[14:15] op_sel_hi:[1,0]
	v_pk_mul_f32 v[10:11], v[158:159], s[14:15] op_sel_hi:[1,0]
	v_cvt_pk_fp8_f32 v12, v8, v9 op_sel:[0,0,1]
	v_cvt_pk_fp8_f32 v13, v10, v11 op_sel:[0,0,1]
	v_pk_mul_f32 v[8:9], v[152:153], s[14:15] op_sel_hi:[1,0]
	v_pk_mul_f32 v[10:11], v[148:149], s[14:15] op_sel_hi:[1,0]
	v_mov_b32_e32 v14, v65
	v_mov_b32_e32 v15, v65
	v_cvt_pk_fp8_f32 v14, v8, v9
	v_cvt_pk_fp8_f32 v15, v10, v11
	v_or_b32_e32 v6, 16, v2
	v_pk_mul_f32 v[8:9], v[154:155], s[14:15] op_sel_hi:[1,0]
	v_pk_mul_f32 v[10:11], v[150:151], s[14:15] op_sel_hi:[1,0]
	v_ashrrev_i32_e32 v7, 31, v6
	v_cvt_pk_fp8_f32 v14, v8, v9 op_sel:[0,0,1]
	v_cvt_pk_fp8_f32 v15, v10, v11 op_sel:[0,0,1]
	v_lshlrev_b64 v[6:7], 13, v[6:7]
	v_lshl_add_u64 v[6:7], v[4:5], 0, v[6:7]
	v_mov_b32_e32 v214, v12
	v_mov_b32_e32 v215, v13
	v_mov_b32_dpp v12, v14 row_ror:8 row_mask:0xf bank_mask:0xc
	v_mov_b32_dpp v13, v15 row_ror:8 row_mask:0xf bank_mask:0xc
	v_mov_b32_dpp v14, v214 row_ror:8 row_mask:0xf bank_mask:0x3
	v_mov_b32_dpp v15, v215 row_ror:8 row_mask:0xf bank_mask:0x3
	v_lshl_add_u64 v[216:217], v[6:7], 0, v[212:213]
	global_store_dwordx2 v[6:7], v[12:13], off
	global_store_dwordx2 v[216:217], v[14:15], off
	v_pk_mul_f32 v[8:9], v[128:129], s[14:15] op_sel_hi:[1,0]
	v_pk_mul_f32 v[10:11], v[124:125], s[14:15] op_sel_hi:[1,0]
	v_mov_b32_e32 v12, v65
	v_mov_b32_e32 v13, v65
	v_cvt_pk_fp8_f32 v12, v8, v9
	v_cvt_pk_fp8_f32 v13, v10, v11
	v_pk_mul_f32 v[8:9], v[130:131], s[14:15] op_sel_hi:[1,0]
	v_pk_mul_f32 v[10:11], v[126:127], s[14:15] op_sel_hi:[1,0]
	v_cvt_pk_fp8_f32 v12, v8, v9 op_sel:[0,0,1]
	v_cvt_pk_fp8_f32 v13, v10, v11 op_sel:[0,0,1]
	v_pk_mul_f32 v[8:9], v[120:121], s[14:15] op_sel_hi:[1,0]
	v_pk_mul_f32 v[10:11], v[116:117], s[14:15] op_sel_hi:[1,0]
	v_mov_b32_e32 v14, v65
	v_mov_b32_e32 v15, v65
	v_cvt_pk_fp8_f32 v14, v8, v9
	v_cvt_pk_fp8_f32 v15, v10, v11
	v_or_b32_e32 v6, 32, v2
	v_pk_mul_f32 v[8:9], v[122:123], s[14:15] op_sel_hi:[1,0]
	v_pk_mul_f32 v[10:11], v[118:119], s[14:15] op_sel_hi:[1,0]
	v_ashrrev_i32_e32 v7, 31, v6
	v_cvt_pk_fp8_f32 v14, v8, v9 op_sel:[0,0,1]
	v_cvt_pk_fp8_f32 v15, v10, v11 op_sel:[0,0,1]
	v_lshlrev_b64 v[6:7], 13, v[6:7]
	v_lshl_add_u64 v[6:7], v[4:5], 0, v[6:7]
	v_mov_b32_e32 v214, v12
	v_mov_b32_e32 v215, v13
	v_mov_b32_dpp v12, v14 row_ror:8 row_mask:0xf bank_mask:0xc
	v_mov_b32_dpp v13, v15 row_ror:8 row_mask:0xf bank_mask:0xc
	v_mov_b32_dpp v14, v214 row_ror:8 row_mask:0xf bank_mask:0x3
	v_mov_b32_dpp v15, v215 row_ror:8 row_mask:0xf bank_mask:0x3
	v_lshl_add_u64 v[216:217], v[6:7], 0, v[212:213]
	global_store_dwordx2 v[6:7], v[12:13], off
	global_store_dwordx2 v[216:217], v[14:15], off
	v_pk_mul_f32 v[6:7], v[96:97], s[14:15] op_sel_hi:[1,0]
	v_pk_mul_f32 v[8:9], v[92:93], s[14:15] op_sel_hi:[1,0]
	v_mov_b32_e32 v10, v65
	v_mov_b32_e32 v11, v65
	v_cvt_pk_fp8_f32 v10, v6, v7
	v_cvt_pk_fp8_f32 v11, v8, v9
	v_pk_mul_f32 v[6:7], v[98:99], s[14:15] op_sel_hi:[1,0]
	v_pk_mul_f32 v[8:9], v[94:95], s[14:15] op_sel_hi:[1,0]
	v_cvt_pk_fp8_f32 v10, v6, v7 op_sel:[0,0,1]
	v_cvt_pk_fp8_f32 v11, v8, v9 op_sel:[0,0,1]
	v_pk_mul_f32 v[6:7], v[88:89], s[14:15] op_sel_hi:[1,0]
	v_pk_mul_f32 v[8:9], v[84:85], s[14:15] op_sel_hi:[1,0]
	v_mov_b32_e32 v12, v65
	v_mov_b32_e32 v13, v65
	v_cvt_pk_fp8_f32 v12, v6, v7
	v_cvt_pk_fp8_f32 v13, v8, v9
;   __device__ __forceinline__ void operator()(const Acc& acc, const GUnit& u, int wr, int wc, int fr, int fq) const {
;     const int row0 = u.pm * 256 + wr * 64 + fr;
;     unsigned char* ob = Q0 + (size_t)u.pn * 256 + wc * 32 + 8 * fq;
; #pragma unroll
;     for (int ai = 0; ai < 2; ++ai)
; #pragma unroll
;       for (int m = 0; m < 4; ++m) {
;         const int row = row0 + ai * 128 + m * 16;
; #pragma unroll
;         for (int bj = 0; bj < 2; ++bj) { const f32x4 a = acc[ai][bj][m][0] * osc, b = acc[ai][bj][m][1] * osc; u32x2 w;
;           w[0] = __builtin_amdgcn_cvt_pk_fp8_f32(a[0], a[1], 0, false); w[0] = __builtin_amdgcn_cvt_pk_fp8_f32(a[2], a[3], w[0], true);
;           w[1] = __builtin_amdgcn_cvt_pk_fp8_f32(b[0], b[1], 0, false); w[1] = __builtin_amdgcn_cvt_pk_fp8_f32(b[2], b[3], w[1], true);
;           *(u32x2*)(ob + (size_t)row * 8192 + bj * 128) = w; }
;       }
	v_or_b32_e32 v2, 48, v2
	v_ashrrev_i32_e32 v3, 31, v2
	v_pk_mul_f32 v[6:7], v[90:91], s[14:15] op_sel_hi:[1,0]
	v_pk_mul_f32 v[8:9], v[86:87], s[14:15] op_sel_hi:[1,0]
	v_lshlrev_b64 v[2:3], 13, v[2:3]
	v_cvt_pk_fp8_f32 v12, v6, v7 op_sel:[0,0,1]
	v_cvt_pk_fp8_f32 v13, v8, v9 op_sel:[0,0,1]
	v_lshl_add_u64 v[2:3], v[4:5], 0, v[2:3]
	v_pk_mul_f32 v[4:5], v[176:177], s[14:15] op_sel_hi:[1,0]
	v_pk_mul_f32 v[6:7], v[172:173], s[14:15] op_sel_hi:[1,0]
	v_mov_b32_e32 v8, v65
	v_mov_b32_e32 v9, v65
	v_cvt_pk_fp8_f32 v8, v4, v5
	v_cvt_pk_fp8_f32 v9, v6, v7
	v_pk_mul_f32 v[4:5], v[178:179], s[14:15] op_sel_hi:[1,0]
	v_pk_mul_f32 v[6:7], v[174:175], s[14:15] op_sel_hi:[1,0]
	v_mov_b32_e32 v214, v10
	v_mov_b32_e32 v215, v11
	v_mov_b32_dpp v10, v12 row_ror:8 row_mask:0xf bank_mask:0xc
	v_mov_b32_dpp v11, v13 row_ror:8 row_mask:0xf bank_mask:0xc
	v_mov_b32_dpp v12, v214 row_ror:8 row_mask:0xf bank_mask:0x3
	v_mov_b32_dpp v13, v215 row_ror:8 row_mask:0xf bank_mask:0x3
	v_lshl_add_u64 v[216:217], v[2:3], 0, v[212:213]
	global_store_dwordx2 v[2:3], v[10:11], off
	global_store_dwordx2 v[216:217], v[12:13], off
	v_cvt_pk_fp8_f32 v8, v4, v5 op_sel:[0,0,1]
	v_cvt_pk_fp8_f32 v9, v6, v7 op_sel:[0,0,1]
	v_pk_mul_f32 v[4:5], v[168:169], s[14:15] op_sel_hi:[1,0]
	v_pk_mul_f32 v[6:7], v[164:165], s[14:15] op_sel_hi:[1,0]
	v_mov_b32_e32 v10, v65
	v_mov_b32_e32 v11, v65
	v_cvt_pk_fp8_f32 v10, v4, v5
	v_cvt_pk_fp8_f32 v11, v6, v7
	v_pk_mul_f32 v[4:5], v[170:171], s[14:15] op_sel_hi:[1,0]
	v_pk_mul_f32 v[6:7], v[166:167], s[14:15] op_sel_hi:[1,0]
	v_cvt_pk_fp8_f32 v10, v4, v5 op_sel:[0,0,1]
	v_cvt_pk_fp8_f32 v11, v6, v7 op_sel:[0,0,1]
	v_add_co_u32_e32 v4, vcc, s54, v0
	v_lshl_add_u64 v[2:3], v[0:1], 0, s[16:17]
	s_nop 0
	v_addc_co_u32_e32 v5, vcc, 0, v1, vcc
	v_mov_b32_e32 v214, v8
	v_mov_b32_e32 v215, v9
	v_mov_b32_dpp v8, v10 row_ror:8 row_mask:0xf bank_mask:0xc
	v_mov_b32_dpp v9, v11 row_ror:8 row_mask:0xf bank_mask:0xc
	v_mov_b32_dpp v10, v214 row_ror:8 row_mask:0xf bank_mask:0x3
	v_mov_b32_dpp v11, v215 row_ror:8 row_mask:0xf bank_mask:0x3
	v_lshl_add_u64 v[216:217], v[4:5], 0, v[212:213]
	global_store_dwordx2 v[4:5], v[8:9], off
	global_store_dwordx2 v[216:217], v[10:11], off
	v_pk_mul_f32 v[4:5], v[144:145], s[14:15] op_sel_hi:[1,0]
	v_pk_mul_f32 v[6:7], v[140:141], s[14:15] op_sel_hi:[1,0]
	v_mov_b32_e32 v8, v65
	v_mov_b32_e32 v9, v65
	v_cvt_pk_fp8_f32 v8, v4, v5
	v_cvt_pk_fp8_f32 v9, v6, v7
	v_pk_mul_f32 v[4:5], v[146:147], s[14:15] op_sel_hi:[1,0]
	v_pk_mul_f32 v[6:7], v[142:143], s[14:15] op_sel_hi:[1,0]
	v_cvt_pk_fp8_f32 v8, v4, v5 op_sel:[0,0,1]
	v_cvt_pk_fp8_f32 v9, v6, v7 op_sel:[0,0,1]
	v_pk_mul_f32 v[4:5], v[136:137], s[14:15] op_sel_hi:[1,0]
	v_pk_mul_f32 v[6:7], v[132:133], s[14:15] op_sel_hi:[1,0]
	v_mov_b32_e32 v10, v65
	v_mov_b32_e32 v11, v65
	v_cvt_pk_fp8_f32 v10, v4, v5
	v_cvt_pk_fp8_f32 v11, v6, v7
	v_pk_mul_f32 v[4:5], v[138:139], s[14:15] op_sel_hi:[1,0]
	v_pk_mul_f32 v[6:7], v[134:135], s[14:15] op_sel_hi:[1,0]
	v_cvt_pk_fp8_f32 v10, v4, v5 op_sel:[0,0,1]
	v_cvt_pk_fp8_f32 v11, v6, v7 op_sel:[0,0,1]
	v_add_co_u32_e32 v4, vcc, s55, v0
	v_lshl_add_u64 v[2:3], v[0:1], 0, s[18:19]
	s_nop 0
	v_addc_co_u32_e32 v5, vcc, 0, v1, vcc
	v_mov_b32_e32 v214, v8
	v_mov_b32_e32 v215, v9
	v_mov_b32_dpp v8, v10 row_ror:8 row_mask:0xf bank_mask:0xc
	v_mov_b32_dpp v9, v11 row_ror:8 row_mask:0xf bank_mask:0xc
	v_mov_b32_dpp v10, v214 row_ror:8 row_mask:0xf bank_mask:0x3
	v_mov_b32_dpp v11, v215 row_ror:8 row_mask:0xf bank_mask:0x3
	v_lshl_add_u64 v[216:217], v[4:5], 0, v[212:213]
	global_store_dwordx2 v[4:5], v[8:9], off
	global_store_dwordx2 v[216:217], v[10:11], off
	v_pk_mul_f32 v[4:5], v[112:113], s[14:15] op_sel_hi:[1,0]
	v_pk_mul_f32 v[6:7], v[108:109], s[14:15] op_sel_hi:[1,0]
	v_mov_b32_e32 v8, v65
	v_mov_b32_e32 v9, v65
	v_cvt_pk_fp8_f32 v8, v4, v5
	v_cvt_pk_fp8_f32 v9, v6, v7
	v_pk_mul_f32 v[4:5], v[114:115], s[14:15] op_sel_hi:[1,0]
	v_pk_mul_f32 v[6:7], v[110:111], s[14:15] op_sel_hi:[1,0]
	v_cvt_pk_fp8_f32 v8, v4, v5 op_sel:[0,0,1]
	v_cvt_pk_fp8_f32 v9, v6, v7 op_sel:[0,0,1]
	v_pk_mul_f32 v[4:5], v[104:105], s[14:15] op_sel_hi:[1,0]
	v_pk_mul_f32 v[6:7], v[100:101], s[14:15] op_sel_hi:[1,0]
	v_mov_b32_e32 v10, v65
	v_mov_b32_e32 v11, v65
	v_cvt_pk_fp8_f32 v10, v4, v5
	v_cvt_pk_fp8_f32 v11, v6, v7
	v_pk_mul_f32 v[4:5], v[106:107], s[14:15] op_sel_hi:[1,0]
	v_pk_mul_f32 v[6:7], v[102:103], s[14:15] op_sel_hi:[1,0]
	v_cvt_pk_fp8_f32 v10, v4, v5 op_sel:[0,0,1]
	v_cvt_pk_fp8_f32 v11, v6, v7 op_sel:[0,0,1]
	v_add_co_u32_e32 v4, vcc, s56, v0
	v_lshl_add_u64 v[2:3], v[0:1], 0, s[20:21]
	s_nop 0
	v_addc_co_u32_e32 v5, vcc, 0, v1, vcc
	v_mov_b32_e32 v214, v8
	v_mov_b32_e32 v215, v9
	v_mov_b32_dpp v8, v10 row_ror:8 row_mask:0xf bank_mask:0xc
	v_mov_b32_dpp v9, v11 row_ror:8 row_mask:0xf bank_mask:0xc
	v_mov_b32_dpp v10, v214 row_ror:8 row_mask:0xf bank_mask:0x3
	v_mov_b32_dpp v11, v215 row_ror:8 row_mask:0xf bank_mask:0x3
	v_lshl_add_u64 v[216:217], v[4:5], 0, v[212:213]
	global_store_dwordx2 v[4:5], v[8:9], off
	global_store_dwordx2 v[216:217], v[10:11], off
	v_pk_mul_f32 v[4:5], v[80:81], s[14:15] op_sel_hi:[1,0]
	v_pk_mul_f32 v[6:7], v[76:77], s[14:15] op_sel_hi:[1,0]
	v_mov_b32_e32 v8, v65
	v_mov_b32_e32 v9, v65
	v_cvt_pk_fp8_f32 v8, v4, v5
	v_cvt_pk_fp8_f32 v9, v6, v7
	v_pk_mul_f32 v[4:5], v[82:83], s[14:15] op_sel_hi:[1,0]
	v_pk_mul_f32 v[6:7], v[78:79], s[14:15] op_sel_hi:[1,0]
	v_cvt_pk_fp8_f32 v8, v4, v5 op_sel:[0,0,1]
	v_cvt_pk_fp8_f32 v9, v6, v7 op_sel:[0,0,1]
	v_pk_mul_f32 v[4:5], v[72:73], s[14:15] op_sel_hi:[1,0]
	v_pk_mul_f32 v[6:7], v[68:69], s[14:15] op_sel_hi:[1,0]
	v_mov_b32_e32 v10, v65
	v_mov_b32_e32 v11, v65
	v_cvt_pk_fp8_f32 v10, v4, v5
	v_cvt_pk_fp8_f32 v11, v6, v7
	v_pk_mul_f32 v[4:5], v[74:75], s[14:15] op_sel_hi:[1,0]
	v_pk_mul_f32 v[6:7], v[70:71], s[14:15] op_sel_hi:[1,0]
	v_lshl_add_u64 v[2:3], v[0:1], 0, s[22:23]
	v_cvt_pk_fp8_f32 v10, v4, v5 op_sel:[0,0,1]
	v_cvt_pk_fp8_f32 v11, v6, v7 op_sel:[0,0,1]
	v_add_co_u32_e32 v0, vcc, s57, v0
	s_mov_b64 s[8:9], -1
	s_nop 0
	v_addc_co_u32_e32 v1, vcc, 0, v1, vcc
	s_andn2_b64 vcc, exec, s[24:25]
	v_mov_b32_e32 v214, v8
	v_mov_b32_e32 v215, v9
	v_mov_b32_dpp v8, v10 row_ror:8 row_mask:0xf bank_mask:0xc
	v_mov_b32_dpp v9, v11 row_ror:8 row_mask:0xf bank_mask:0xc
	v_mov_b32_dpp v10, v214 row_ror:8 row_mask:0xf bank_mask:0x3
	v_mov_b32_dpp v11, v215 row_ror:8 row_mask:0xf bank_mask:0x3
	v_lshl_add_u64 v[216:217], v[0:1], 0, v[212:213]
	global_store_dwordx2 v[0:1], v[8:9], off
	global_store_dwordx2 v[216:217], v[10:11], off
	s_cbranch_vccnz .LBB0_954
	s_andn2_b64 vcc, exec, s[10:11]
	s_cbranch_vccnz .LBB0_953
	s_barrier
	s_branch .LBB0_953
